# v68 stack + P1 derived-vector block rewritten straight-line with all 7 loads in flight (1 round trip instead of 3)
# speedup vs baseline: 1.0061x; 1.0061x over previous
.LBB0_53:
	s_waitcnt vmcnt(0) lgkmcnt(0)
	s_add_u32 s0, s10, 0x14000
	s_addc_u32 s1, s11, 0
	s_add_u32 s8, s10, 0x100000
	s_addc_u32 s9, s11, 0
	v_add_u32_e32 v7, 0x2000, v2
	v_add_u32_e32 v9, 0x4000, v2
	v_add_u32_e32 v12, 0x6000, v2
	global_load_dword v13, v2, s[46:47]
	global_load_dword v14, v2, s[0:1]
	global_load_dword v15, v9, s[0:1]
	global_load_dword v10, v2, s[12:13]
	global_load_dword v16, v7, s[0:1]
	global_load_dword v11, v12, s[0:1]
	global_load_dword v6, v2, s[14:15]
	s_waitcnt vmcnt(0)
	v_mul_f32_e32 v13, v14, v13
	v_add_f32_e32 v15, 1.0, v15
	v_mul_f32_e32 v6, v11, v6
	global_store_dword v2, v13, s[8:9]
	v_mul_f32_e32 v10, v10, v15
	global_store_dword v9, v16, s[8:9]
	global_store_dword v7, v10, s[8:9]
	global_store_dword v12, v6, s[8:9]
	s_cmpk_gt_i32 s76, 0x1fff
	s_cbranch_scc1 .LBB0_57
